# MLA attention softmax: packed s-m and packed row-sum as in the band loop (32 sub + 32 add -> 16 + 17)
# speedup vs baseline: 1.0002x; 1.0002x over previous
.LBB0_1614:
	v_pk_add_f32 v[66:67], v[66:67], v[234:235] op_sel:[0,1] op_sel_hi:[1,1] neg_lo:[0,1] neg_hi:[0,1]
	v_pk_add_f32 v[68:69], v[68:69], v[234:235] op_sel:[0,1] op_sel_hi:[1,1] neg_lo:[0,1] neg_hi:[0,1]
	v_pk_add_f32 v[70:71], v[70:71], v[234:235] op_sel:[0,1] op_sel_hi:[1,1] neg_lo:[0,1] neg_hi:[0,1]
	v_pk_add_f32 v[72:73], v[72:73], v[234:235] op_sel:[0,1] op_sel_hi:[1,1] neg_lo:[0,1] neg_hi:[0,1]
	v_pk_add_f32 v[74:75], v[74:75], v[234:235] op_sel:[0,1] op_sel_hi:[1,1] neg_lo:[0,1] neg_hi:[0,1]
	v_pk_add_f32 v[76:77], v[76:77], v[234:235] op_sel:[0,1] op_sel_hi:[1,1] neg_lo:[0,1] neg_hi:[0,1]
	v_pk_add_f32 v[78:79], v[78:79], v[234:235] op_sel:[0,1] op_sel_hi:[1,1] neg_lo:[0,1] neg_hi:[0,1]
	v_pk_add_f32 v[80:81], v[80:81], v[234:235] op_sel:[0,1] op_sel_hi:[1,1] neg_lo:[0,1] neg_hi:[0,1]
	v_pk_add_f32 v[82:83], v[82:83], v[234:235] op_sel:[0,1] op_sel_hi:[1,1] neg_lo:[0,1] neg_hi:[0,1]
	v_pk_add_f32 v[84:85], v[84:85], v[234:235] op_sel:[0,1] op_sel_hi:[1,1] neg_lo:[0,1] neg_hi:[0,1]
	v_pk_add_f32 v[86:87], v[86:87], v[234:235] op_sel:[0,1] op_sel_hi:[1,1] neg_lo:[0,1] neg_hi:[0,1]
	v_pk_add_f32 v[88:89], v[88:89], v[234:235] op_sel:[0,1] op_sel_hi:[1,1] neg_lo:[0,1] neg_hi:[0,1]
	v_pk_add_f32 v[90:91], v[90:91], v[234:235] op_sel:[0,1] op_sel_hi:[1,1] neg_lo:[0,1] neg_hi:[0,1]
	v_pk_add_f32 v[92:93], v[92:93], v[234:235] op_sel:[0,1] op_sel_hi:[1,1] neg_lo:[0,1] neg_hi:[0,1]
	v_pk_add_f32 v[94:95], v[94:95], v[234:235] op_sel:[0,1] op_sel_hi:[1,1] neg_lo:[0,1] neg_hi:[0,1]
	v_pk_add_f32 v[96:97], v[96:97], v[234:235] op_sel:[0,1] op_sel_hi:[1,1] neg_lo:[0,1] neg_hi:[0,1]
	v_exp_f32_e32 v236, v66
	v_exp_f32_e32 v237, v67
	v_exp_f32_e32 v238, v68
	v_exp_f32_e32 v239, v69
	v_exp_f32_e32 v240, v70
	v_exp_f32_e32 v241, v71
	v_exp_f32_e32 v243, v72
	v_exp_f32_e32 v244, v73
	v_exp_f32_e32 v245, v74
	v_exp_f32_e32 v246, v75
	v_exp_f32_e32 v247, v76
	v_exp_f32_e32 v248, v77
	v_exp_f32_e32 v249, v78
	v_exp_f32_e32 v250, v79
	v_exp_f32_e32 v251, v80
	v_exp_f32_e32 v252, v81
	v_exp_f32_e32 v82, v82
	v_exp_f32_e32 v83, v83
	v_pk_add_f32 v[66:67], v[236:237], v[238:239]
	v_exp_f32_e32 v84, v84
	v_exp_f32_e32 v85, v85
	v_pk_add_f32 v[66:67], v[66:67], v[240:241]
	v_pk_add_f32 v[66:67], v[66:67], v[82:83]
	v_exp_f32_e32 v86, v86
	v_exp_f32_e32 v87, v87
	v_pk_add_f32 v[66:67], v[66:67], v[244:245]
	v_pk_add_f32 v[66:67], v[66:67], v[84:85]
	v_exp_f32_e32 v88, v88
	v_exp_f32_e32 v89, v89
	v_pk_add_f32 v[66:67], v[66:67], v[246:247]
	v_pk_add_f32 v[66:67], v[66:67], v[86:87]
	v_exp_f32_e32 v90, v90
	v_exp_f32_e32 v91, v91
	v_pk_add_f32 v[66:67], v[66:67], v[248:249]
	v_pk_add_f32 v[66:67], v[66:67], v[88:89]
	v_exp_f32_e32 v92, v92
	v_exp_f32_e32 v93, v93
	v_pk_add_f32 v[66:67], v[66:67], v[250:251]
	v_pk_add_f32 v[66:67], v[66:67], v[90:91]
	v_exp_f32_e32 v94, v94
	v_exp_f32_e32 v95, v95
	v_pk_add_f32 v[66:67], v[66:67], v[92:93]
	v_exp_f32_e32 v96, v96
	v_exp_f32_e32 v97, v97
	v_pk_add_f32 v[66:67], v[66:67], v[94:95]
	s_nop 0
	v_pk_add_f32 v[66:67], v[66:67], v[96:97]
	v_add_f32_e32 v66, v66, v67
	v_add_f32_e32 v66, v243, v66
	v_add_f32_e32 v253, v252, v66
	v_cvt_pk_bf16_f32 v66, v82, v83
	v_cvt_pk_bf16_f32 v67, v84, v85
	ds_read_b64_tr_b16 v[78:79], v227 offset:25600
	ds_read_b64_tr_b16 v[80:81], v227 offset:26880
	ds_read_b64_tr_b16 v[84:85], v227 offset:26944
	ds_read_b64_tr_b16 v[82:83], v227 offset:25664
	v_fmac_f32_e32 v253, v234, v218
	v_cvt_pk_bf16_f32 v68, v86, v87
	v_cvt_pk_bf16_f32 v69, v88, v89
	v_cvt_pk_bf16_f32 v70, v90, v91
	v_cvt_pk_bf16_f32 v71, v92, v93
	v_cvt_pk_bf16_f32 v72, v94, v95
	v_cvt_pk_bf16_f32 v73, v96, v97
	v_cvt_pk_bf16_f32 v74, v236, v237
	v_cvt_pk_bf16_f32 v75, v238, v239
	v_cvt_pk_bf16_f32 v76, v240, v241
	v_cvt_pk_bf16_f32 v77, v243, v244
	v_cvt_pk_bf16_f32 v86, v245, v246
	v_cvt_pk_bf16_f32 v87, v247, v248
	v_cvt_pk_bf16_f32 v88, v249, v250
	v_cvt_pk_bf16_f32 v89, v251, v252
	s_waitcnt lgkmcnt(2)
	v_mfma_f32_32x32x16_bf16 v[50:65], v[78:81], v[66:69], v[50:65]
	ds_read_b64_tr_b16 v[90:91], v227 offset:25728
	ds_read_b64_tr_b16 v[92:93], v227 offset:27008
	s_waitcnt lgkmcnt(2)
	v_mfma_f32_32x32x16_bf16 v[34:49], v[82:85], v[66:69], v[34:49]
	ds_read_b64_tr_b16 v[78:79], v227 offset:25792
	ds_read_b64_tr_b16 v[80:81], v227 offset:27072
	s_waitcnt lgkmcnt(2)
	v_mfma_f32_32x32x16_bf16 v[18:33], v[90:93], v[66:69], v[18:33]
	ds_read_b64_tr_b16 v[82:83], v227 offset:30720
	ds_read_b64_tr_b16 v[84:85], v227 offset:32000
	s_waitcnt lgkmcnt(2)
	v_mfma_f32_32x32x16_bf16 v[2:17], v[78:81], v[66:69], v[2:17]
	ds_read_b64_tr_b16 v[90:91], v227 offset:30784
	ds_read_b64_tr_b16 v[92:93], v227 offset:32064
	s_waitcnt lgkmcnt(2)
	v_mfma_f32_32x32x16_bf16 v[50:65], v[82:85], v[70:73], v[50:65]
	ds_read_b64_tr_b16 v[66:67], v227 offset:30848
	ds_read_b64_tr_b16 v[68:69], v227 offset:32128
	s_waitcnt lgkmcnt(2)
	v_mfma_f32_32x32x16_bf16 v[34:49], v[90:93], v[70:73], v[34:49]
	ds_read_b64_tr_b16 v[78:79], v227 offset:30912
	ds_read_b64_tr_b16 v[80:81], v227 offset:32192
	s_waitcnt lgkmcnt(2)
	v_mfma_f32_32x32x16_bf16 v[18:33], v[66:69], v[70:73], v[18:33]
	ds_read_b64_tr_b16 v[82:83], v227 offset:35840
	ds_read_b64_tr_b16 v[84:85], v227 offset:37120
	s_waitcnt lgkmcnt(2)
	v_mfma_f32_32x32x16_bf16 v[2:17], v[78:81], v[70:73], v[2:17]
	ds_read_b64_tr_b16 v[66:67], v227 offset:35904
	ds_read_b64_tr_b16 v[68:69], v227 offset:37184
	s_waitcnt lgkmcnt(2)
	v_mfma_f32_32x32x16_bf16 v[50:65], v[82:85], v[74:77], v[50:65]
	ds_read_b64_tr_b16 v[70:71], v227 offset:35968
	ds_read_b64_tr_b16 v[72:73], v227 offset:37248
	s_waitcnt lgkmcnt(2)
	v_mfma_f32_32x32x16_bf16 v[34:49], v[66:69], v[74:77], v[34:49]
	ds_read_b64_tr_b16 v[78:79], v227 offset:36032
	ds_read_b64_tr_b16 v[80:81], v227 offset:37312
	s_waitcnt lgkmcnt(2)
	v_mfma_f32_32x32x16_bf16 v[18:33], v[70:73], v[74:77], v[18:33]
	ds_read_b64_tr_b16 v[66:67], v227 offset:40960
	ds_read_b64_tr_b16 v[68:69], v227 offset:42240
	s_waitcnt lgkmcnt(2)
	v_mfma_f32_32x32x16_bf16 v[2:17], v[78:81], v[74:77], v[2:17]
	ds_read_b64_tr_b16 v[70:71], v227 offset:41024
	ds_read_b64_tr_b16 v[72:73], v227 offset:42304
	s_waitcnt lgkmcnt(2)
	v_mfma_f32_32x32x16_bf16 v[50:65], v[66:69], v[86:89], v[50:65]
	ds_read_b64_tr_b16 v[74:75], v227 offset:41088
	ds_read_b64_tr_b16 v[76:77], v227 offset:42368
	s_waitcnt lgkmcnt(2)
	v_mfma_f32_32x32x16_bf16 v[34:49], v[70:73], v[86:89], v[34:49]
	ds_read_b64_tr_b16 v[66:67], v227 offset:41152
	ds_read_b64_tr_b16 v[68:69], v227 offset:42432
	s_waitcnt lgkmcnt(2)
	v_mfma_f32_32x32x16_bf16 v[18:33], v[74:77], v[86:89], v[18:33]
	s_waitcnt lgkmcnt(0)
	v_mfma_f32_32x32x16_bf16 v[2:17], v[66:69], v[86:89], v[2:17]
	v_mov_b32_e32 v234, v253
	s_branch .LBB0_1616
